# SWA: batched K/V staging loads; bias/mask lookup as 16 unconditional ds_read + cndmask instead of 16 exec-masked round trips
# speedup vs baseline: 1.0190x; 1.0190x over previous
.LBB0_148:
	s_ashr_i32 s13, s24, 31
	s_ashr_i32 s12, s24, 2
	s_lshr_b32 s13, s13, 26
	s_add_i32 s13, s12, s13
	s_ashr_i32 s22, s13, 6
	s_andn2_b32 s13, s13, 63
	s_sub_i32 s13, s12, s13
	s_and_b32 s25, s24, 3
	s_lshl_b32 s12, s13, 8
	s_cmp_eq_u32 s13, 0
	s_cselect_b32 s30, 0x80, 0
	s_ashr_i32 s23, s22, 31
	s_lshl_b64 s[22:23], s[22:23], 14
	s_ashr_i32 s13, s12, 31
	s_lshl_b32 s31, s25, 6
	s_barrier
	s_add_u32 s44, s22, s12
	s_addc_u32 s45, s23, s13
	s_lshl_b64 s[44:45], s[44:45], 9
	s_add_u32 s37, s82, s44
	s_addc_u32 s41, s83, s45
	s_lshl_b32 s44, s31, 1
	s_add_u32 s44, s37, s44
	s_addc_u32 s45, s41, 0
	v_mov_b32_e32 v75, v135
	v_lshl_add_u64 v[2:3], s[44:45], 0, v[74:75]
	s_mov_b64 s[44:45], 0xa1f0000
	v_lshl_add_u64 v[2:3], v[2:3], 0, s[44:45]
	v_ashrrev_i32_e32 v134, 3, v130
	v_lshlrev_b64 v[6:7], 9, v[134:135]
	v_lshl_add_u64 v[6:7], v[2:3], 0, v[6:7]
	v_mad_u32_u24 v226, v134, s29, v70
	s_mov_b64 s[44:45], 0x8000
	global_load_dwordx4 v[178:181], v[6:7], off
	v_lshl_add_u64 v[6:7], v[6:7], 0, s[44:45]
	global_load_dwordx4 v[182:185], v[6:7], off
	v_lshl_add_u64 v[6:7], v[6:7], 0, s[44:45]
	global_load_dwordx4 v[186:189], v[6:7], off
	v_lshl_add_u64 v[6:7], v[6:7], 0, s[44:45]
	global_load_dwordx4 v[190:193], v[6:7], off
	v_lshl_add_u64 v[6:7], v[6:7], 0, s[44:45]
	global_load_dwordx4 v[194:197], v[6:7], off
	v_lshl_add_u64 v[6:7], v[6:7], 0, s[44:45]
	global_load_dwordx4 v[198:201], v[6:7], off
	s_lshl_b32 s31, s31, 16
	s_add_u32 s31, s82, s31
	s_addc_u32 s37, s83, 0
	s_lshl_b64 s[44:45], s[22:23], 1
	s_add_u32 s31, s31, s44
	s_addc_u32 s37, s37, s45
	s_lshl_b64 s[44:45], s[12:13], 1
	s_add_u32 s13, s31, s44
	s_addc_u32 s31, s37, s45
	s_add_u32 s44, s13, 0xb1fff00
	s_addc_u32 s45, s31, 0
	s_movk_i32 s46, 0xfe80
	s_movk_i32 s47, 0x308
	s_mov_b32 s50, 0xd800
	v_mov_b32_e32 v240, v130
	v_mul_hi_i32 v241, v240, s17
	v_ashrrev_i32_e32 v241, 4, v241
	v_lshlrev_b32_e32 v242, 2, v240
	v_mad_i32_i24 v242, v241, s46, v242
	v_lshlrev_b32_e32 v243, 16, v241
	v_lshl_add_u32 v243, v242, 1, v243
	global_load_dwordx2 v[202:203], v243, s[44:45]
	v_lshl_add_u32 v244, v242, 1, s50
	v_mad_u32_u24 v228, v241, s47, v244
	v_add_u32_e32 v240, 0x200, v130
	v_mul_hi_i32 v241, v240, s17
	v_ashrrev_i32_e32 v241, 4, v241
	v_lshlrev_b32_e32 v242, 2, v240
	v_mad_i32_i24 v242, v241, s46, v242
	v_lshlrev_b32_e32 v243, 16, v241
	v_lshl_add_u32 v243, v242, 1, v243
	global_load_dwordx2 v[204:205], v243, s[44:45]
	v_lshl_add_u32 v244, v242, 1, s50
	v_mad_u32_u24 v229, v241, s47, v244
	v_add_u32_e32 v240, 0x400, v130
	v_mul_hi_i32 v241, v240, s17
	v_ashrrev_i32_e32 v241, 4, v241
	v_lshlrev_b32_e32 v242, 2, v240
	v_mad_i32_i24 v242, v241, s46, v242
	v_lshlrev_b32_e32 v243, 16, v241
	v_lshl_add_u32 v243, v242, 1, v243
	global_load_dwordx2 v[206:207], v243, s[44:45]
	v_lshl_add_u32 v244, v242, 1, s50
	v_mad_u32_u24 v230, v241, s47, v244
	v_add_u32_e32 v240, 0x600, v130
	v_mul_hi_i32 v241, v240, s17
	v_ashrrev_i32_e32 v241, 4, v241
	v_lshlrev_b32_e32 v242, 2, v240
	v_mad_i32_i24 v242, v241, s46, v242
	v_lshlrev_b32_e32 v243, 16, v241
	v_lshl_add_u32 v243, v242, 1, v243
	global_load_dwordx2 v[208:209], v243, s[44:45]
	v_lshl_add_u32 v244, v242, 1, s50
	v_mad_u32_u24 v231, v241, s47, v244
	v_add_u32_e32 v240, 0x800, v130
	v_mul_hi_i32 v241, v240, s17
	v_ashrrev_i32_e32 v241, 4, v241
	v_lshlrev_b32_e32 v242, 2, v240
	v_mad_i32_i24 v242, v241, s46, v242
	v_lshlrev_b32_e32 v243, 16, v241
	v_lshl_add_u32 v243, v242, 1, v243
	global_load_dwordx2 v[210:211], v243, s[44:45]
	v_lshl_add_u32 v244, v242, 1, s50
	v_mad_u32_u24 v232, v241, s47, v244
	v_add_u32_e32 v240, 0xa00, v130
	v_mul_hi_i32 v241, v240, s17
	v_ashrrev_i32_e32 v241, 4, v241
	v_lshlrev_b32_e32 v242, 2, v240
	v_mad_i32_i24 v242, v241, s46, v242
	v_lshlrev_b32_e32 v243, 16, v241
	v_lshl_add_u32 v243, v242, 1, v243
	global_load_dwordx2 v[212:213], v243, s[44:45]
	v_lshl_add_u32 v244, v242, 1, s50
	v_mad_u32_u24 v233, v241, s47, v244
	v_add_u32_e32 v240, 0xc00, v130
	v_mul_hi_i32 v241, v240, s17
	v_ashrrev_i32_e32 v241, 4, v241
	v_lshlrev_b32_e32 v242, 2, v240
	v_mad_i32_i24 v242, v241, s46, v242
	v_lshlrev_b32_e32 v243, 16, v241
	v_lshl_add_u32 v243, v242, 1, v243
	global_load_dwordx2 v[214:215], v243, s[44:45]
	v_lshl_add_u32 v244, v242, 1, s50
	v_mad_u32_u24 v234, v241, s47, v244
	v_add_u32_e32 v240, 0xe00, v130
	v_mul_hi_i32 v241, v240, s17
	v_ashrrev_i32_e32 v241, 4, v241
	v_lshlrev_b32_e32 v242, 2, v240
	v_mad_i32_i24 v242, v241, s46, v242
	v_lshlrev_b32_e32 v243, 16, v241
	v_lshl_add_u32 v243, v242, 1, v243
	global_load_dwordx2 v[216:217], v243, s[44:45]
	v_lshl_add_u32 v244, v242, 1, s50
	v_mad_u32_u24 v235, v241, s47, v244
	v_add_u32_e32 v240, 0x1000, v130
	v_mul_hi_i32 v241, v240, s17
	v_ashrrev_i32_e32 v241, 4, v241
	v_lshlrev_b32_e32 v242, 2, v240
	v_mad_i32_i24 v242, v241, s46, v242
	v_lshlrev_b32_e32 v243, 16, v241
	v_lshl_add_u32 v243, v242, 1, v243
	global_load_dwordx2 v[218:219], v243, s[44:45]
	v_lshl_add_u32 v244, v242, 1, s50
	v_mad_u32_u24 v236, v241, s47, v244
	v_add_u32_e32 v240, 0x1200, v130
	v_mul_hi_i32 v241, v240, s17
	v_ashrrev_i32_e32 v241, 4, v241
	v_lshlrev_b32_e32 v242, 2, v240
	v_mad_i32_i24 v242, v241, s46, v242
	v_lshlrev_b32_e32 v243, 16, v241
	v_lshl_add_u32 v243, v242, 1, v243
	global_load_dwordx2 v[220:221], v243, s[44:45]
	v_lshl_add_u32 v244, v242, 1, s50
	v_mad_u32_u24 v237, v241, s47, v244
	v_add_u32_e32 v240, 0x1400, v130
	v_mul_hi_i32 v241, v240, s17
	v_ashrrev_i32_e32 v241, 4, v241
	v_lshlrev_b32_e32 v242, 2, v240
	v_mad_i32_i24 v242, v241, s46, v242
	v_lshlrev_b32_e32 v243, 16, v241
	v_lshl_add_u32 v243, v242, 1, v243
	global_load_dwordx2 v[222:223], v243, s[44:45]
	v_lshl_add_u32 v244, v242, 1, s50
	v_mad_u32_u24 v238, v241, s47, v244
	v_add_u32_e32 v240, 0x1600, v130
	v_mul_hi_i32 v241, v240, s17
	v_ashrrev_i32_e32 v241, 4, v241
	v_lshlrev_b32_e32 v242, 2, v240
	v_mad_i32_i24 v242, v241, s46, v242
	v_lshlrev_b32_e32 v243, 16, v241
	v_lshl_add_u32 v243, v242, 1, v243
	global_load_dwordx2 v[224:225], v243, s[44:45]
	v_lshl_add_u32 v244, v242, 1, s50
	v_mad_u32_u24 v239, v241, s47, v244
	s_waitcnt vmcnt(17)
	ds_write_b128 v226, v[178:181]
	s_waitcnt vmcnt(16)
	ds_write_b128 v226, v[182:185] offset:9216
	s_waitcnt vmcnt(15)
	ds_write_b128 v226, v[186:189] offset:18432
	s_waitcnt vmcnt(14)
	ds_write_b128 v226, v[190:193] offset:27648
	s_waitcnt vmcnt(13)
	ds_write_b128 v226, v[194:197] offset:36864
	s_waitcnt vmcnt(12)
	ds_write_b128 v226, v[198:201] offset:46080
	s_waitcnt vmcnt(11)
	ds_write_b64 v228, v[202:203]
	s_waitcnt vmcnt(10)
	ds_write_b64 v229, v[204:205]
	s_waitcnt vmcnt(9)
	ds_write_b64 v230, v[206:207]
	s_waitcnt vmcnt(8)
	ds_write_b64 v231, v[208:209]
	s_waitcnt vmcnt(7)
	ds_write_b64 v232, v[210:211]
	s_waitcnt vmcnt(6)
	ds_write_b64 v233, v[212:213]
	s_waitcnt vmcnt(5)
	ds_write_b64 v234, v[214:215]
	s_waitcnt vmcnt(4)
	ds_write_b64 v235, v[216:217]
	s_waitcnt vmcnt(3)
	ds_write_b64 v236, v[218:219]
	s_waitcnt vmcnt(2)
	ds_write_b64 v237, v[220:221]
	s_waitcnt vmcnt(1)
	ds_write_b64 v238, v[222:223]
	s_waitcnt vmcnt(0)
	ds_write_b64 v239, v[224:225]
.LBB0_158:
	s_and_b32 s13, s21, 3
	s_add_i32 s12, s12, s19
	s_mul_i32 s26, s13, 0x600
	s_ashr_i32 s13, s12, 31
	s_add_u32 s22, s22, s12
	s_addc_u32 s13, s23, s13
	v_mov_b32_e32 v3, s13
	s_sub_i32 s13, 0x80, s12
	s_ashr_i32 s13, s13, 5
	s_cmpk_lt_i32 s12, 0x80
	v_or_b32_e32 v2, s22, v66
	s_cselect_b32 s22, s13, 0
	s_cmp_gt_i32 s22, 4
	s_cselect_b64 s[12:13], -1, 0
	s_add_i32 s23, s38, s22
	v_lshlrev_b64 v[2:3], 11, v[2:3]
	s_mul_i32 s27, s23, 0x1200
	v_lshl_add_u64 v[76:77], v[68:69], 0, v[2:3]
	v_lshl_add_u64 v[78:79], v[72:73], 0, v[2:3]
	s_add_i32 s31, s22, -1
	v_add_u32_e32 v75, s27, v71
	s_lshl_b32 s27, s22, 5
	v_add_u32_e32 v2, s26, v81
	s_lshl_b32 s22, s22, 7
	v_subrev_u32_e32 v85, s22, v2
	s_lshl_b32 s22, s23, 6
	s_mul_i32 s25, s25, 3
	s_mov_b32 s30, 0
	v_subrev_u32_e32 v84, s27, v80
	v_add_u32_e32 v86, s22, v82
	v_add_u32_e32 v87, s22, v83
	s_waitcnt lgkmcnt(0)
	s_barrier
	s_branch .LBB0_161

.LBB0_165:
	v_add_u32_e32 v100, 0, v92
	ds_read_b128 v[34:37], v100
	ds_read_b128 v[96:99], v100 offset:32
	s_waitcnt lgkmcnt(1)
	v_mfma_f32_32x32x16_bf16 v[34:49], v[34:37], v[50:53], 0
	s_waitcnt lgkmcnt(0)
	v_mfma_f32_32x32x16_bf16 v[34:49], v[96:99], v[54:57], v[34:49]
	ds_read_b128 v[96:99], v100 offset:64
	s_waitcnt vmcnt(1) lgkmcnt(0)
	v_mfma_f32_32x32x16_bf16 v[34:49], v[96:99], v[58:61], v[34:49]
	ds_read_b128 v[96:99], v100 offset:96
	s_waitcnt vmcnt(0) lgkmcnt(0)
	v_mfma_f32_32x32x16_bf16 v[34:49], v[96:99], v[62:65], v[34:49]
	v_add_u32_e32 v98, 0x19b94, v90
	ds_read_b32 v112, v98 offset:108
	ds_read_b32 v113, v98 offset:104
	ds_read_b32 v114, v98 offset:100
	ds_read_b32 v115, v98 offset:96
	ds_read_b32 v116, v98 offset:76
	ds_read_b32 v117, v98 offset:72
	ds_read_b32 v118, v98 offset:68
	ds_read_b32 v119, v98 offset:64
	ds_read_b32 v120, v98 offset:44
	ds_read_b32 v121, v98 offset:40
	ds_read_b32 v122, v98 offset:36
	ds_read_b32 v123, v98 offset:32
	ds_read_b32 v124, v98 offset:12
	ds_read_b32 v125, v98 offset:8
	ds_read_b32 v126, v98 offset:4
	ds_read_b32 v127, v98
	v_mov_b32_e32 v128, 0xf149f2ca
	v_add_u32_e32 v129, 27, v91
	s_waitcnt lgkmcnt(0)
	v_cmp_gt_u32_e32 vcc, s49, v129
	v_add_f32_e32 v112, v34, v112
	v_add_u32_e32 v129, 26, v91
	v_cndmask_b32_e32 v97, v128, v112, vcc
	v_cmp_gt_u32_e32 vcc, s49, v129
	v_add_f32_e32 v113, v35, v113
	v_add_u32_e32 v129, 25, v91
	v_cndmask_b32_e32 v96, v128, v113, vcc
	v_cmp_gt_u32_e32 vcc, s49, v129
	v_add_f32_e32 v114, v36, v114
	v_add_u32_e32 v129, 24, v91
	v_cndmask_b32_e32 v99, v128, v114, vcc
	v_cmp_gt_u32_e32 vcc, s49, v129
	v_add_f32_e32 v115, v37, v115
	v_add_u32_e32 v129, 19, v91
	v_cndmask_b32_e32 v35, v128, v115, vcc
	v_cmp_gt_u32_e32 vcc, s49, v129
	v_add_f32_e32 v116, v38, v116
	v_add_u32_e32 v129, 18, v91
	v_cndmask_b32_e32 v37, v128, v116, vcc
	v_cmp_gt_u32_e32 vcc, s49, v129
	v_add_f32_e32 v117, v39, v117
	v_add_u32_e32 v129, 17, v91
	v_cndmask_b32_e32 v36, v128, v117, vcc
	v_cmp_gt_u32_e32 vcc, s49, v129
	v_add_f32_e32 v118, v40, v118
	v_add_u32_e32 v129, 16, v91
	v_cndmask_b32_e32 v100, v128, v118, vcc
	v_cmp_gt_u32_e32 vcc, s49, v129
	v_add_f32_e32 v119, v41, v119
	v_add_u32_e32 v129, 11, v91
	v_cndmask_b32_e32 v39, v128, v119, vcc
	v_cmp_gt_u32_e32 vcc, s49, v129
	v_add_f32_e32 v120, v42, v120
	v_add_u32_e32 v129, 10, v91
	v_cndmask_b32_e32 v41, v128, v120, vcc
	v_cmp_gt_u32_e32 vcc, s49, v129
	v_add_f32_e32 v121, v43, v121
	v_add_u32_e32 v129, 9, v91
	v_cndmask_b32_e32 v40, v128, v121, vcc
	v_cmp_gt_u32_e32 vcc, s49, v129
	v_add_f32_e32 v122, v44, v122
	v_add_u32_e32 v129, 8, v91
	v_cndmask_b32_e32 v43, v128, v122, vcc
	v_cmp_gt_u32_e32 vcc, s49, v129
	v_add_f32_e32 v123, v45, v123
	v_add_u32_e32 v129, 3, v91
	v_cndmask_b32_e32 v42, v128, v123, vcc
	v_cmp_gt_u32_e32 vcc, s49, v129
	v_add_f32_e32 v124, v46, v124
	v_add_u32_e32 v129, 2, v91
	v_cndmask_b32_e32 v45, v128, v124, vcc
	v_cmp_gt_u32_e32 vcc, s49, v129
	v_add_f32_e32 v125, v47, v125
	v_add_u32_e32 v129, 1, v91
	v_cndmask_b32_e32 v44, v128, v125, vcc
	v_cmp_gt_u32_e32 vcc, s49, v129
	v_add_f32_e32 v126, v48, v126
	v_mov_b32_e32 v129, v91
	v_cndmask_b32_e32 v46, v128, v126, vcc
	v_cmp_gt_u32_e32 vcc, s49, v129
	v_add_f32_e32 v127, v49, v127
	s_nop 0
	v_cndmask_b32_e32 v38, v128, v127, vcc
	v_max_f32_e32 v34, v96, v96
	v_max_f32_e32 v47, v97, v97
	v_max_f32_e32 v34, v47, v34
	v_max3_f32 v34, v34, v99, v35
	v_max3_f32 v34, v34, v37, v36
	v_max3_f32 v34, v34, v100, v39
	v_max3_f32 v34, v34, v41, v40
	v_max3_f32 v34, v34, v43, v42
	v_max3_f32 v34, v34, v45, v44
	v_max3_f32 v34, v34, v46, v38
	ds_bpermute_b32 v47, v93, v34
	v_add_u32_e32 v111, 0, v88
	s_add_i32 s26, s26, 1
	v_add_u32_e32 v92, 0x1200, v92
	v_subrev_u32_e32 v91, 32, v91
	s_waitcnt lgkmcnt(0)
	v_max3_f32 v34, v95, v34, v47
	v_sub_f32_e32 v36, v36, v34
	v_exp_f32_e32 v103, v36
	v_sub_f32_e32 v36, v100, v34
	v_exp_f32_e32 v100, v36
	v_sub_f32_e32 v36, v39, v34
	v_exp_f32_e32 v104, v36
	v_sub_f32_e32 v36, v41, v34
	v_exp_f32_e32 v105, v36
	v_sub_f32_e32 v36, v40, v34
	v_exp_f32_e32 v106, v36
	v_sub_f32_e32 v36, v43, v34
	v_exp_f32_e32 v107, v36
	v_sub_f32_e32 v36, v42, v34
	v_sub_f32_e32 v48, v97, v34
	v_sub_f32_e32 v37, v37, v34
	v_exp_f32_e32 v108, v36
	v_sub_f32_e32 v36, v45, v34
	v_sub_f32_e32 v47, v95, v34
	v_exp_f32_e32 v95, v48
	v_sub_f32_e32 v48, v99, v34
	v_exp_f32_e32 v102, v37
	v_exp_f32_e32 v109, v36
	v_sub_f32_e32 v36, v44, v34
	v_add_u32_e32 v37, 0, v89
	v_sub_f32_e32 v49, v96, v34
	v_exp_f32_e32 v101, v48
	v_exp_f32_e32 v48, v47
	v_exp_f32_e32 v110, v36
	v_sub_f32_e32 v36, v46, v34
	ds_read2_b64 v[44:47], v37 offset1:2
	ds_read2_b64 v[96:99], v111 offset1:2
	v_sub_f32_e32 v35, v35, v34
	v_exp_f32_e32 v49, v49
	v_exp_f32_e32 v35, v35
	v_cvt_pk_bf16_f32 v42, v102, v103
	v_cvt_pk_bf16_f32 v43, v100, v104
	v_pk_mul_f32 v[32:33], v[32:33], v[48:49] op_sel_hi:[1,0]
	v_pk_mul_f32 v[30:31], v[30:31], v[48:49] op_sel_hi:[1,0]
	v_cvt_pk_bf16_f32 v40, v95, v49
	v_cvt_pk_bf16_f32 v41, v101, v35
	v_pk_mul_f32 v[16:17], v[16:17], v[48:49] op_sel_hi:[1,0]
	v_pk_mul_f32 v[14:15], v[14:15], v[48:49] op_sel_hi:[1,0]
	v_pk_mul_f32 v[12:13], v[12:13], v[48:49] op_sel_hi:[1,0]
	v_pk_mul_f32 v[10:11], v[10:11], v[48:49] op_sel_hi:[1,0]
	v_pk_mul_f32 v[8:9], v[8:9], v[48:49] op_sel_hi:[1,0]
	v_pk_mul_f32 v[6:7], v[6:7], v[48:49] op_sel_hi:[1,0]
	v_pk_mul_f32 v[4:5], v[4:5], v[48:49] op_sel_hi:[1,0]
	v_pk_mul_f32 v[2:3], v[2:3], v[48:49] op_sel_hi:[1,0]
	v_pk_mul_f32 v[28:29], v[28:29], v[48:49] op_sel_hi:[1,0]
	v_pk_mul_f32 v[26:27], v[26:27], v[48:49] op_sel_hi:[1,0]
	v_pk_mul_f32 v[24:25], v[24:25], v[48:49] op_sel_hi:[1,0]
	v_pk_mul_f32 v[22:23], v[22:23], v[48:49] op_sel_hi:[1,0]
	v_pk_mul_f32 v[20:21], v[20:21], v[48:49] op_sel_hi:[1,0]
	v_pk_mul_f32 v[18:19], v[18:19], v[48:49] op_sel_hi:[1,0]
	s_waitcnt lgkmcnt(1)
	v_mfma_f32_32x32x16_bf16 v[2:17], v[44:47], v[40:43], v[2:17]
	ds_read2_b64 v[44:47], v37 offset0:4 offset1:6
	v_cvt_pk_bf16_f32 v37, v107, v108
	v_add_u32_e32 v90, 0xffffff80, v90
	v_add_u32_e32 v89, 64, v89
	s_cmp_lt_i32 s26, 4
	v_add_u32_e32 v88, 64, v88
	s_waitcnt lgkmcnt(1)
	v_mfma_f32_32x32x16_bf16 v[18:33], v[96:99], v[40:43], v[18:33]
	ds_read2_b64 v[40:43], v111 offset0:4 offset1:6
	v_exp_f32_e32 v96, v36
	v_sub_f32_e32 v36, v38, v34
	v_exp_f32_e32 v97, v36
	v_cvt_pk_bf16_f32 v36, v105, v106
	v_cvt_pk_bf16_f32 v38, v109, v110
	v_cvt_pk_bf16_f32 v39, v96, v97
	s_waitcnt lgkmcnt(1)
	s_nop 0
	v_mfma_f32_32x32x16_bf16 v[2:17], v[44:47], v[36:39], v[2:17]
	s_waitcnt lgkmcnt(0)
	v_mfma_f32_32x32x16_bf16 v[18:33], v[40:43], v[36:39], v[18:33]
	v_add_f32_e32 v36, 0, v95
	v_add_f32_e32 v36, v49, v36
	v_add_f32_e32 v36, v101, v36
	v_add_f32_e32 v35, v35, v36
	v_add_f32_e32 v35, v102, v35
	v_add_f32_e32 v35, v103, v35
	v_add_f32_e32 v35, v100, v35
	v_add_f32_e32 v35, v104, v35
	v_add_f32_e32 v35, v105, v35
	v_add_f32_e32 v35, v106, v35
	v_add_f32_e32 v35, v107, v35
	v_add_f32_e32 v35, v108, v35
	v_add_f32_e32 v35, v109, v35
	v_add_f32_e32 v35, v110, v35
	v_add_f32_e32 v35, v96, v35
	v_add_f32_e32 v35, v97, v35
	v_fmac_f32_e32 v35, v94, v48
	s_cbranch_scc0 .LBB0_159
	v_mov_b32_e32 v95, v34
	v_mov_b32_e32 v94, v35
	s_branch .LBB0_165
